# NA: one static s_setprio 1 for waves 4-7 during the neighbourhood-attention units
# baseline (speedup 1.0000x reference)
.LBB0_1225:
	s_setprio 0
	v_readfirstlane_b32 s98, v206
	s_nop 0
	s_lshr_b32 s98, s98, 8
	s_cmp_eq_u32 s98, 0
	s_cbranch_scc1 .Lna_prio_skip
	s_setprio 1

.LBB0_1267:
	s_setprio 0
	s_mov_b32 s48, s49
	s_mov_b32 s18, s79
	s_waitcnt vmcnt(0)
	s_waitcnt vmcnt(0)
	s_barrier
	s_and_saveexec_b64 s[0:1], s[92:93]
	v_readlane_b32 s58, v254, 32
	v_readlane_b32 s34, v254, 29
	v_readlane_b32 s33, v254, 30
	s_mov_b64 s[36:37], 0x100
	v_readlane_b32 s59, v254, 33
	s_cbranch_execz .LBB0_1319
	v_readlane_b32 s4, v253, 55
	s_lshl_b64 s[2:3], s[48:49], 2
	s_waitcnt vmcnt(0) expcnt(0) lgkmcnt(0)
	v_mov_b32_e32 v0, s4
	v_readlane_b32 s4, v252, 1
	ds_read_b32 v2, v0
	s_add_u32 s2, s4, s2
	v_readlane_b32 s4, v253, 56
	v_readlane_b32 s5, v252, 2
	s_addc_u32 s3, s5, s3
	v_mov_b32_e32 v0, s4
	ds_read_b32 v0, v0
	s_waitcnt lgkmcnt(1)
	v_cmp_ne_u32_e32 vcc, 0, v2
	s_cbranch_vccnz .LBB0_1283
	s_add_u32 s4, s2, 0x1000
	s_addc_u32 s5, s3, 0
	s_add_u32 s6, s2, 0x1100
	s_addc_u32 s7, s3, 0
	s_add_u32 s8, s2, 0x1200
	s_addc_u32 s9, s3, 0
	s_add_u32 s10, s2, 0x1300
	s_addc_u32 s11, s3, 0
	s_mov_b32 s19, 1
	s_branch .LBB0_1271
